# gate/up GEMM K-loop: 8 phases merged into 4 (32 MFMAs per barrier interval), DMA refills re-slotted, uniform vmcnt(8)
# baseline (speedup 1.0000x reference)
.LBB0_297:
	s_add_u32 s22, s20, 0xfffc0080
	s_addc_u32 s23, s21, -1
	s_add_i32 s49, 0, 0x10000
	v_add_u32_e32 v145, s49, v142
	ds_read_b128 v[146:149], v145
	ds_read_b128 v[150:153], v145 offset:1024
	ds_read_b128 v[154:157], v145 offset:2048
	ds_read_b128 v[158:161], v145 offset:3072
	s_cmp_eq_u32 s48, 12
	s_cselect_b32 s25, s9, s23
	s_cselect_b32 s24, s44, s22
	s_cselect_b32 s23, s7, s47
	s_cselect_b32 s22, s45, s46
	s_add_i32 m0, s19, 0xc000
	ds_read_b128 v[162:165], v144
	ds_read_b128 v[166:169], v144 offset:1024
	ds_read_b128 v[170:173], v144 offset:2048
	ds_read_b128 v[174:177], v144 offset:3072
	ds_read_b128 v[190:193], v144 offset:4096
	ds_read_b128 v[194:197], v144 offset:5120
	ds_read_b128 v[198:201], v144 offset:6144
	ds_read_b128 v[202:205], v144 offset:7168
	global_load_lds_dwordx4 v138, s[20:21]
	s_add_i32 m0, s19, 0xe000
	s_nop 0
	global_load_lds_dwordx4 v140, s[20:21]
	s_add_i32 s54, 0, 0x14000
	v_add_u32_e32 v145, s54, v142
	ds_read_b128 v[206:209], v145
	ds_read_b128 v[210:213], v145 offset:1024
	ds_read_b128 v[214:217], v145 offset:2048
	ds_read_b128 v[218:221], v145 offset:3072
	s_waitcnt vmcnt(8)
	s_waitcnt lgkmcnt(0)
	s_barrier
	v_mfma_f32_16x16x32_bf16 v[126:129], v[146:149], v[162:165], v[126:129]
	v_mfma_f32_16x16x32_bf16 v[118:121], v[154:157], v[162:165], v[118:121]
	v_mfma_f32_16x16x32_bf16 v[110:113], v[146:149], v[170:173], v[110:113]
	v_mfma_f32_16x16x32_bf16 v[102:105], v[154:157], v[170:173], v[102:105]
	v_mfma_f32_16x16x32_bf16 v[94:97], v[146:149], v[190:193], v[94:97]
	v_mfma_f32_16x16x32_bf16 v[86:89], v[154:157], v[190:193], v[86:89]
	v_mfma_f32_16x16x32_bf16 v[78:81], v[146:149], v[198:201], v[78:81]
	v_mfma_f32_16x16x32_bf16 v[70:73], v[154:157], v[198:201], v[70:73]
	v_mfma_f32_16x16x32_bf16 v[126:129], v[150:153], v[166:169], v[126:129]
	v_mfma_f32_16x16x32_bf16 v[118:121], v[158:161], v[166:169], v[118:121]
	v_mfma_f32_16x16x32_bf16 v[110:113], v[150:153], v[174:177], v[110:113]
	v_mfma_f32_16x16x32_bf16 v[102:105], v[158:161], v[174:177], v[102:105]
	v_mfma_f32_16x16x32_bf16 v[94:97], v[150:153], v[194:197], v[94:97]
	v_mfma_f32_16x16x32_bf16 v[86:89], v[158:161], v[194:197], v[86:89]
	v_mfma_f32_16x16x32_bf16 v[78:81], v[150:153], v[202:205], v[78:81]
	v_mfma_f32_16x16x32_bf16 v[70:73], v[158:161], v[202:205], v[70:73]
	v_mfma_f32_16x16x32_bf16 v[122:125], v[206:209], v[162:165], v[122:125]
	v_mfma_f32_16x16x32_bf16 v[114:117], v[214:217], v[162:165], v[114:117]
	v_mfma_f32_16x16x32_bf16 v[106:109], v[206:209], v[170:173], v[106:109]
	v_mfma_f32_16x16x32_bf16 v[98:101], v[214:217], v[170:173], v[98:101]
	v_mfma_f32_16x16x32_bf16 v[90:93], v[206:209], v[190:193], v[90:93]
	v_mfma_f32_16x16x32_bf16 v[82:85], v[214:217], v[190:193], v[82:85]
	v_mfma_f32_16x16x32_bf16 v[74:77], v[206:209], v[198:201], v[74:77]
	v_mfma_f32_16x16x32_bf16 v[66:69], v[214:217], v[198:201], v[66:69]
	v_mfma_f32_16x16x32_bf16 v[122:125], v[210:213], v[166:169], v[122:125]
	v_mfma_f32_16x16x32_bf16 v[114:117], v[218:221], v[166:169], v[114:117]
	v_mfma_f32_16x16x32_bf16 v[106:109], v[210:213], v[174:177], v[106:109]
	v_mfma_f32_16x16x32_bf16 v[98:101], v[218:221], v[174:177], v[98:101]
	v_mfma_f32_16x16x32_bf16 v[90:93], v[210:213], v[194:197], v[90:93]
	v_mfma_f32_16x16x32_bf16 v[82:85], v[218:221], v[194:197], v[82:85]
	v_mfma_f32_16x16x32_bf16 v[74:77], v[210:213], v[202:205], v[74:77]
	v_mfma_f32_16x16x32_bf16 v[66:69], v[218:221], v[202:205], v[66:69]
	s_barrier
	ds_read_b128 v[162:165], v144 offset:16384
	ds_read_b128 v[166:169], v144 offset:17408
	ds_read_b128 v[170:173], v144 offset:18432
	ds_read_b128 v[174:177], v144 offset:19456
	ds_read_b128 v[190:193], v144 offset:20480
	ds_read_b128 v[194:197], v144 offset:21504
	ds_read_b128 v[198:201], v144 offset:22528
	ds_read_b128 v[202:205], v144 offset:23552
	s_add_i32 s49, s49, s35
	s_add_u32 s64, s22, 0x80
	s_addc_u32 s65, s23, 0
	s_mov_b32 m0, s49
	s_nop 0
	global_load_lds_dwordx4 v134, s[22:23]
	s_add_i32 m0, s49, 0x2000
	s_nop 0
	global_load_lds_dwordx4 v130, s[22:23]
	s_mov_b32 m0, s19
	s_add_u32 s62, s24, 0x80
	s_addc_u32 s63, s25, 0
	global_load_lds_dwordx4 v136, s[24:25]
	s_mov_b32 m0, s36
	s_nop 0
	global_load_lds_dwordx4 v132, s[24:25]
	s_add_u32 s50, s22, 0x40000
	s_addc_u32 s51, s23, 0
	s_add_i32 s49, s54, s35
	s_mov_b32 m0, s49
	s_nop 0
	global_load_lds_dwordx4 v134, s[50:51]
	s_add_i32 m0, s49, 0x2000
	s_nop 0
	global_load_lds_dwordx4 v130, s[50:51]
	s_waitcnt vmcnt(8)
	s_waitcnt lgkmcnt(0)
	s_barrier
	v_mfma_f32_16x16x32_bf16 v[62:65], v[146:149], v[162:165], v[62:65]
	v_mfma_f32_16x16x32_bf16 v[54:57], v[154:157], v[162:165], v[54:57]
	v_mfma_f32_16x16x32_bf16 v[46:49], v[146:149], v[170:173], v[46:49]
	v_mfma_f32_16x16x32_bf16 v[38:41], v[154:157], v[170:173], v[38:41]
	v_mfma_f32_16x16x32_bf16 v[30:33], v[146:149], v[190:193], v[30:33]
	v_mfma_f32_16x16x32_bf16 v[22:25], v[154:157], v[190:193], v[22:25]
	v_mfma_f32_16x16x32_bf16 v[14:17], v[146:149], v[198:201], v[14:17]
	v_mfma_f32_16x16x32_bf16 v[6:9], v[154:157], v[198:201], v[6:9]
	v_mfma_f32_16x16x32_bf16 v[62:65], v[150:153], v[166:169], v[62:65]
	v_mfma_f32_16x16x32_bf16 v[54:57], v[158:161], v[166:169], v[54:57]
	v_mfma_f32_16x16x32_bf16 v[46:49], v[150:153], v[174:177], v[46:49]
	v_mfma_f32_16x16x32_bf16 v[38:41], v[158:161], v[174:177], v[38:41]
	v_mfma_f32_16x16x32_bf16 v[30:33], v[150:153], v[194:197], v[30:33]
	v_mfma_f32_16x16x32_bf16 v[22:25], v[158:161], v[194:197], v[22:25]
	v_mfma_f32_16x16x32_bf16 v[14:17], v[150:153], v[202:205], v[14:17]
	v_mfma_f32_16x16x32_bf16 v[6:9], v[158:161], v[202:205], v[6:9]
	v_mfma_f32_16x16x32_bf16 v[58:61], v[206:209], v[162:165], v[58:61]
	v_mfma_f32_16x16x32_bf16 v[50:53], v[214:217], v[162:165], v[50:53]
	v_mfma_f32_16x16x32_bf16 v[42:45], v[206:209], v[170:173], v[42:45]
	v_mfma_f32_16x16x32_bf16 v[34:37], v[214:217], v[170:173], v[34:37]
	v_mfma_f32_16x16x32_bf16 v[26:29], v[206:209], v[190:193], v[26:29]
	v_mfma_f32_16x16x32_bf16 v[18:21], v[214:217], v[190:193], v[18:21]
	v_mfma_f32_16x16x32_bf16 v[10:13], v[206:209], v[198:201], v[10:13]
	v_mfma_f32_16x16x32_bf16 v[2:5], v[214:217], v[198:201], v[2:5]
	v_mfma_f32_16x16x32_bf16 v[58:61], v[210:213], v[166:169], v[58:61]
	v_mfma_f32_16x16x32_bf16 v[50:53], v[218:221], v[166:169], v[50:53]
	v_mfma_f32_16x16x32_bf16 v[42:45], v[210:213], v[174:177], v[42:45]
	v_mfma_f32_16x16x32_bf16 v[34:37], v[218:221], v[174:177], v[34:37]
	v_mfma_f32_16x16x32_bf16 v[26:29], v[210:213], v[194:197], v[26:29]
	v_mfma_f32_16x16x32_bf16 v[18:21], v[218:221], v[194:197], v[18:21]
	v_mfma_f32_16x16x32_bf16 v[10:13], v[210:213], v[202:205], v[10:13]
	v_mfma_f32_16x16x32_bf16 v[2:5], v[218:221], v[202:205], v[2:5]
	s_barrier
	s_add_i32 s49, 0, 0x18000
	v_add_u32_e32 v145, s49, v142
	ds_read_b128 v[146:149], v145
	ds_read_b128 v[150:153], v145 offset:1024
	ds_read_b128 v[154:157], v145 offset:2048
	ds_read_b128 v[158:161], v145 offset:3072
	s_add_u32 s24, s24, 0x40000
	s_addc_u32 s25, s25, 0
	s_mov_b32 m0, s37
	ds_read_b128 v[162:165], v144 offset:32768
	ds_read_b128 v[166:169], v144 offset:33792
	ds_read_b128 v[170:173], v144 offset:34816
	ds_read_b128 v[174:177], v144 offset:35840
	ds_read_b128 v[190:193], v144 offset:36864
	ds_read_b128 v[194:197], v144 offset:37888
	ds_read_b128 v[198:201], v144 offset:38912
	ds_read_b128 v[202:205], v144 offset:39936
	global_load_lds_dwordx4 v136, s[24:25]
	s_mov_b32 m0, s38
	s_nop 0
	global_load_lds_dwordx4 v132, s[24:25]
	s_add_i32 s24, 0, 0x1c000
	v_add_u32_e32 v145, s24, v142
	ds_read_b128 v[206:209], v145
	ds_read_b128 v[210:213], v145 offset:1024
	ds_read_b128 v[214:217], v145 offset:2048
	ds_read_b128 v[218:221], v145 offset:3072
	s_waitcnt vmcnt(8)
	s_waitcnt lgkmcnt(0)
	s_barrier
	v_mfma_f32_16x16x32_bf16 v[126:129], v[146:149], v[162:165], v[126:129]
	v_mfma_f32_16x16x32_bf16 v[118:121], v[154:157], v[162:165], v[118:121]
	v_mfma_f32_16x16x32_bf16 v[110:113], v[146:149], v[170:173], v[110:113]
	v_mfma_f32_16x16x32_bf16 v[102:105], v[154:157], v[170:173], v[102:105]
	v_mfma_f32_16x16x32_bf16 v[94:97], v[146:149], v[190:193], v[94:97]
	v_mfma_f32_16x16x32_bf16 v[86:89], v[154:157], v[190:193], v[86:89]
	v_mfma_f32_16x16x32_bf16 v[78:81], v[146:149], v[198:201], v[78:81]
	v_mfma_f32_16x16x32_bf16 v[70:73], v[154:157], v[198:201], v[70:73]
	v_mfma_f32_16x16x32_bf16 v[126:129], v[150:153], v[166:169], v[126:129]
	v_mfma_f32_16x16x32_bf16 v[118:121], v[158:161], v[166:169], v[118:121]
	v_mfma_f32_16x16x32_bf16 v[110:113], v[150:153], v[174:177], v[110:113]
	v_mfma_f32_16x16x32_bf16 v[102:105], v[158:161], v[174:177], v[102:105]
	v_mfma_f32_16x16x32_bf16 v[94:97], v[150:153], v[194:197], v[94:97]
	v_mfma_f32_16x16x32_bf16 v[86:89], v[158:161], v[194:197], v[86:89]
	v_mfma_f32_16x16x32_bf16 v[78:81], v[150:153], v[202:205], v[78:81]
	v_mfma_f32_16x16x32_bf16 v[70:73], v[158:161], v[202:205], v[70:73]
	v_mfma_f32_16x16x32_bf16 v[122:125], v[206:209], v[162:165], v[122:125]
	v_mfma_f32_16x16x32_bf16 v[114:117], v[214:217], v[162:165], v[114:117]
	v_mfma_f32_16x16x32_bf16 v[106:109], v[206:209], v[170:173], v[106:109]
	v_mfma_f32_16x16x32_bf16 v[98:101], v[214:217], v[170:173], v[98:101]
	v_mfma_f32_16x16x32_bf16 v[90:93], v[206:209], v[190:193], v[90:93]
	v_mfma_f32_16x16x32_bf16 v[82:85], v[214:217], v[190:193], v[82:85]
	v_mfma_f32_16x16x32_bf16 v[74:77], v[206:209], v[198:201], v[74:77]
	v_mfma_f32_16x16x32_bf16 v[66:69], v[214:217], v[198:201], v[66:69]
	v_mfma_f32_16x16x32_bf16 v[122:125], v[210:213], v[166:169], v[122:125]
	v_mfma_f32_16x16x32_bf16 v[114:117], v[218:221], v[166:169], v[114:117]
	v_mfma_f32_16x16x32_bf16 v[106:109], v[210:213], v[174:177], v[106:109]
	v_mfma_f32_16x16x32_bf16 v[98:101], v[218:221], v[174:177], v[98:101]
	v_mfma_f32_16x16x32_bf16 v[90:93], v[210:213], v[194:197], v[90:93]
	v_mfma_f32_16x16x32_bf16 v[82:85], v[218:221], v[194:197], v[82:85]
	v_mfma_f32_16x16x32_bf16 v[74:77], v[210:213], v[202:205], v[74:77]
	v_mfma_f32_16x16x32_bf16 v[66:69], v[218:221], v[202:205], v[66:69]
	s_barrier
	ds_read_b128 v[162:165], v144 offset:49152
	ds_read_b128 v[166:169], v144 offset:50176
	ds_read_b128 v[170:173], v144 offset:51200
	ds_read_b128 v[174:177], v144 offset:52224
	ds_read_b128 v[190:193], v144 offset:53248
	ds_read_b128 v[194:197], v144 offset:54272
	ds_read_b128 v[198:201], v144 offset:55296
	ds_read_b128 v[202:205], v144 offset:56320
	s_add_i32 s25, s49, s35
	s_mov_b32 m0, s25
	s_nop 0
	global_load_lds_dwordx4 v134, s[64:65]
	s_add_i32 m0, s25, 0x2000
	s_nop 0
	global_load_lds_dwordx4 v130, s[64:65]
	s_mov_b32 m0, s39
	s_nop 0
	global_load_lds_dwordx4 v136, s[62:63]
	s_mov_b32 m0, s40
	s_nop 0
	global_load_lds_dwordx4 v132, s[62:63]
	s_add_u32 s22, s22, 0x40080
	s_addc_u32 s23, s23, 0
	s_add_i32 s24, s24, s35
	s_mov_b32 m0, s24
	s_nop 0
	global_load_lds_dwordx4 v134, s[22:23]
	s_add_i32 m0, s24, 0x2000
	s_nop 0
	global_load_lds_dwordx4 v130, s[22:23]
	s_waitcnt vmcnt(8)
	s_waitcnt lgkmcnt(0)
	s_barrier
	v_mfma_f32_16x16x32_bf16 v[62:65], v[146:149], v[162:165], v[62:65]
	v_mfma_f32_16x16x32_bf16 v[54:57], v[154:157], v[162:165], v[54:57]
	v_mfma_f32_16x16x32_bf16 v[46:49], v[146:149], v[170:173], v[46:49]
	v_mfma_f32_16x16x32_bf16 v[38:41], v[154:157], v[170:173], v[38:41]
	v_mfma_f32_16x16x32_bf16 v[30:33], v[146:149], v[190:193], v[30:33]
	v_mfma_f32_16x16x32_bf16 v[22:25], v[154:157], v[190:193], v[22:25]
	v_mfma_f32_16x16x32_bf16 v[14:17], v[146:149], v[198:201], v[14:17]
	v_mfma_f32_16x16x32_bf16 v[6:9], v[154:157], v[198:201], v[6:9]
	v_mfma_f32_16x16x32_bf16 v[62:65], v[150:153], v[166:169], v[62:65]
	v_mfma_f32_16x16x32_bf16 v[54:57], v[158:161], v[166:169], v[54:57]
	v_mfma_f32_16x16x32_bf16 v[46:49], v[150:153], v[174:177], v[46:49]
	v_mfma_f32_16x16x32_bf16 v[38:41], v[158:161], v[174:177], v[38:41]
	v_mfma_f32_16x16x32_bf16 v[30:33], v[150:153], v[194:197], v[30:33]
	v_mfma_f32_16x16x32_bf16 v[22:25], v[158:161], v[194:197], v[22:25]
	v_mfma_f32_16x16x32_bf16 v[14:17], v[150:153], v[202:205], v[14:17]
	v_mfma_f32_16x16x32_bf16 v[6:9], v[158:161], v[202:205], v[6:9]
	v_mfma_f32_16x16x32_bf16 v[58:61], v[206:209], v[162:165], v[58:61]
	v_mfma_f32_16x16x32_bf16 v[50:53], v[214:217], v[162:165], v[50:53]
	v_mfma_f32_16x16x32_bf16 v[42:45], v[206:209], v[170:173], v[42:45]
	v_mfma_f32_16x16x32_bf16 v[34:37], v[214:217], v[170:173], v[34:37]
	v_mfma_f32_16x16x32_bf16 v[26:29], v[206:209], v[190:193], v[26:29]
	v_mfma_f32_16x16x32_bf16 v[18:21], v[214:217], v[190:193], v[18:21]
	v_mfma_f32_16x16x32_bf16 v[10:13], v[206:209], v[198:201], v[10:13]
	v_mfma_f32_16x16x32_bf16 v[2:5], v[214:217], v[198:201], v[2:5]
	v_mfma_f32_16x16x32_bf16 v[58:61], v[210:213], v[166:169], v[58:61]
	v_mfma_f32_16x16x32_bf16 v[50:53], v[218:221], v[166:169], v[50:53]
	v_mfma_f32_16x16x32_bf16 v[42:45], v[210:213], v[174:177], v[42:45]
	v_mfma_f32_16x16x32_bf16 v[34:37], v[218:221], v[174:177], v[34:37]
	v_mfma_f32_16x16x32_bf16 v[26:29], v[210:213], v[194:197], v[26:29]
	v_mfma_f32_16x16x32_bf16 v[18:21], v[218:221], v[194:197], v[18:21]
	v_mfma_f32_16x16x32_bf16 v[10:13], v[210:213], v[202:205], v[10:13]
	v_mfma_f32_16x16x32_bf16 v[2:5], v[218:221], v[202:205], v[2:5]
	s_barrier
	s_add_i32 s48, s48, 2
	s_add_u32 s20, s20, 0x100
	s_addc_u32 s21, s21, 0
	s_add_u32 s46, s46, 0x100
	s_addc_u32 s47, s47, 0
	s_cmp_gt_u32 s48, 13
	s_cbranch_scc0 .LBB0_297
	v_mul_f32_e32 v148, 0xbfb8aa3b, v126
	v_mul_f32_e32 v149, 0xbfb8aa3b, v127
	v_exp_f32_e32 v148, v148
	v_exp_f32_e32 v149, v149
	v_lshl_or_b32 v146, s43, 7, v143
	v_lshl_add_u32 v145, s18, 8, v1
	v_add_f32_e32 v148, 1.0, v148
	v_add_f32_e32 v149, 1.0, v149
	v_rcp_f32_e32 v148, v148
	v_rcp_f32_e32 v149, v149
	v_ashrrev_i32_e32 v147, 31, v146
	s_movk_i32 s7, 0x1700
	s_and_b64 vcc, exec, s[4:5]
	v_pk_mul_f32 v[126:127], v[126:127], v[148:149]
	s_mov_b32 s43, s6
	v_pk_mul_f32 v[122:123], v[126:127], v[122:123]
	v_mul_f32_e32 v126, 0xbfb8aa3b, v128
	v_mul_f32_e32 v127, 0xbfb8aa3b, v129
	v_exp_f32_e32 v126, v126
	v_exp_f32_e32 v127, v127
	s_mov_b32 s18, s8
	s_mov_b64 s[22:23], s[14:15]
	v_add_f32_e32 v126, 1.0, v126
	v_add_f32_e32 v127, 1.0, v127
	v_rcp_f32_e32 v126, v126
	v_rcp_f32_e32 v127, v127
	s_nop 0
	v_pk_mul_f32 v[126:127], v[128:129], v[126:127]
	s_nop 0
	v_pk_mul_f32 v[124:125], v[126:127], v[124:125]
	v_mul_f32_e32 v126, 0xbfb8aa3b, v118
	v_mul_f32_e32 v127, 0xbfb8aa3b, v119
	v_exp_f32_e32 v126, v126
	v_exp_f32_e32 v127, v127
	v_add_f32_e32 v126, 1.0, v126
	v_add_f32_e32 v127, 1.0, v127
	v_rcp_f32_e32 v126, v126
	v_rcp_f32_e32 v127, v127
	s_nop 0
	v_pk_mul_f32 v[118:119], v[118:119], v[126:127]
	s_nop 0
	v_pk_mul_f32 v[114:115], v[118:119], v[114:115]
	v_mul_f32_e32 v118, 0xbfb8aa3b, v120
	v_mul_f32_e32 v119, 0xbfb8aa3b, v121
	v_exp_f32_e32 v118, v118
	v_exp_f32_e32 v119, v119
	v_add_f32_e32 v118, 1.0, v118
	v_add_f32_e32 v119, 1.0, v119
	v_rcp_f32_e32 v118, v118
	v_rcp_f32_e32 v119, v119
	s_nop 0
	v_pk_mul_f32 v[118:119], v[120:121], v[118:119]
	s_nop 0
	v_pk_mul_f32 v[116:117], v[118:119], v[116:117]
	v_cvt_pk_bf16_f32 v120, v114, v115
	v_mov_b64_e32 v[114:115], s[2:3]
	v_cvt_pk_bf16_f32 v118, v122, v123
	v_cvt_pk_bf16_f32 v121, v116, v117
	v_mad_i64_i32 v[122:123], s[20:21], v145, s7, v[114:115]
	v_lshlrev_b64 v[116:117], 1, v[146:147]
	v_cvt_pk_bf16_f32 v119, v124, v125
	v_lshl_add_u64 v[122:123], v[122:123], 0, v[116:117]
	global_store_dwordx4 v[122:123], v[118:121], off
	s_nop 1
	v_mul_f32_e32 v118, 0xbfb8aa3b, v110
	v_mul_f32_e32 v119, 0xbfb8aa3b, v111
	v_exp_f32_e32 v118, v118
	v_exp_f32_e32 v119, v119
	v_add_f32_e32 v118, 1.0, v118
	v_add_f32_e32 v119, 1.0, v119
	v_rcp_f32_e32 v118, v118
	v_rcp_f32_e32 v119, v119
	s_nop 0
	v_pk_mul_f32 v[110:111], v[110:111], v[118:119]
	s_nop 0
	v_pk_mul_f32 v[106:107], v[110:111], v[106:107]
	v_mul_f32_e32 v110, 0xbfb8aa3b, v112
	v_mul_f32_e32 v111, 0xbfb8aa3b, v113
	v_exp_f32_e32 v110, v110
	v_exp_f32_e32 v111, v111
	v_add_f32_e32 v110, 1.0, v110
	v_add_f32_e32 v111, 1.0, v111
	v_rcp_f32_e32 v110, v110
	v_rcp_f32_e32 v111, v111
	s_nop 0
	v_pk_mul_f32 v[110:111], v[112:113], v[110:111]
	s_nop 0
	v_pk_mul_f32 v[108:109], v[110:111], v[108:109]
	v_mul_f32_e32 v110, 0xbfb8aa3b, v102
	v_mul_f32_e32 v111, 0xbfb8aa3b, v103
	v_exp_f32_e32 v110, v110
	v_exp_f32_e32 v111, v111
	v_add_f32_e32 v110, 1.0, v110
	v_add_f32_e32 v111, 1.0, v111
	v_rcp_f32_e32 v110, v110
	v_rcp_f32_e32 v111, v111
	s_nop 0
	v_pk_mul_f32 v[102:103], v[102:103], v[110:111]
	s_nop 0
	v_pk_mul_f32 v[102:103], v[102:103], v[98:99]
	v_mul_f32_e32 v98, 0xbfb8aa3b, v104
	v_mul_f32_e32 v99, 0xbfb8aa3b, v105
	v_exp_f32_e32 v98, v98
	v_exp_f32_e32 v99, v99
	v_add_f32_e32 v98, 1.0, v98
	v_add_f32_e32 v99, 1.0, v99
	v_rcp_f32_e32 v98, v98
	v_rcp_f32_e32 v99, v99
	s_nop 0
	v_pk_mul_f32 v[98:99], v[104:105], v[98:99]
	s_nop 0
	v_pk_mul_f32 v[104:105], v[98:99], v[100:101]
	v_cvt_pk_bf16_f32 v100, v102, v103
	v_or_b32_e32 v102, 16, v145
	v_mad_i64_i32 v[102:103], s[20:21], v102, s7, v[114:115]
	v_cvt_pk_bf16_f32 v98, v106, v107
	v_cvt_pk_bf16_f32 v99, v108, v109
	v_cvt_pk_bf16_f32 v101, v104, v105
	v_lshl_add_u64 v[102:103], v[102:103], 0, v[116:117]
	global_store_dwordx4 v[102:103], v[98:101], off
	s_nop 1
	v_mul_f32_e32 v98, 0xbfb8aa3b, v94
	v_mul_f32_e32 v99, 0xbfb8aa3b, v95
	v_exp_f32_e32 v98, v98
	v_exp_f32_e32 v99, v99
	v_add_f32_e32 v98, 1.0, v98
	v_add_f32_e32 v99, 1.0, v99
	v_rcp_f32_e32 v98, v98
	v_rcp_f32_e32 v99, v99
	s_nop 0
	v_pk_mul_f32 v[94:95], v[94:95], v[98:99]
	s_nop 0
	v_pk_mul_f32 v[90:91], v[94:95], v[90:91]
	v_mul_f32_e32 v94, 0xbfb8aa3b, v96
	v_mul_f32_e32 v95, 0xbfb8aa3b, v97
	v_exp_f32_e32 v94, v94
	v_exp_f32_e32 v95, v95
	v_add_f32_e32 v94, 1.0, v94
	v_add_f32_e32 v95, 1.0, v95
	v_rcp_f32_e32 v94, v94
	v_rcp_f32_e32 v95, v95
	s_nop 0
	v_pk_mul_f32 v[94:95], v[96:97], v[94:95]
	s_nop 0
	v_pk_mul_f32 v[92:93], v[94:95], v[92:93]
	v_mul_f32_e32 v94, 0xbfb8aa3b, v86
	v_mul_f32_e32 v95, 0xbfb8aa3b, v87
	v_exp_f32_e32 v94, v94
	v_exp_f32_e32 v95, v95
	v_add_f32_e32 v94, 1.0, v94
	v_add_f32_e32 v95, 1.0, v95
	v_rcp_f32_e32 v94, v94
	v_rcp_f32_e32 v95, v95
	s_nop 0
	v_pk_mul_f32 v[86:87], v[86:87], v[94:95]
	s_nop 0
	v_pk_mul_f32 v[86:87], v[86:87], v[82:83]
	v_mul_f32_e32 v82, 0xbfb8aa3b, v88
	v_mul_f32_e32 v83, 0xbfb8aa3b, v89
	v_exp_f32_e32 v82, v82
	v_exp_f32_e32 v83, v83
	v_add_f32_e32 v82, 1.0, v82
	v_add_f32_e32 v83, 1.0, v83
	v_rcp_f32_e32 v82, v82
	v_rcp_f32_e32 v83, v83
	s_nop 0
	v_pk_mul_f32 v[82:83], v[88:89], v[82:83]
	s_nop 0
	v_pk_mul_f32 v[88:89], v[82:83], v[84:85]
	v_cvt_pk_bf16_f32 v84, v86, v87
	v_or_b32_e32 v86, 32, v145
	v_mad_i64_i32 v[86:87], s[20:21], v86, s7, v[114:115]
	v_cvt_pk_bf16_f32 v82, v90, v91
	v_cvt_pk_bf16_f32 v83, v92, v93
	v_cvt_pk_bf16_f32 v85, v88, v89
	v_lshl_add_u64 v[86:87], v[86:87], 0, v[116:117]
	global_store_dwordx4 v[86:87], v[82:85], off
	s_nop 1
	v_mul_f32_e32 v82, 0xbfb8aa3b, v78
	v_mul_f32_e32 v83, 0xbfb8aa3b, v79
	v_exp_f32_e32 v82, v82
	v_exp_f32_e32 v83, v83
	v_add_f32_e32 v82, 1.0, v82
	v_add_f32_e32 v83, 1.0, v83
	v_rcp_f32_e32 v82, v82
	v_rcp_f32_e32 v83, v83
	s_nop 0
	v_pk_mul_f32 v[78:79], v[78:79], v[82:83]
	s_nop 0
	v_pk_mul_f32 v[74:75], v[78:79], v[74:75]
	v_mul_f32_e32 v78, 0xbfb8aa3b, v80
	v_mul_f32_e32 v79, 0xbfb8aa3b, v81
	v_exp_f32_e32 v78, v78
	v_exp_f32_e32 v79, v79
	v_add_f32_e32 v78, 1.0, v78
	v_add_f32_e32 v79, 1.0, v79
	v_rcp_f32_e32 v78, v78
	v_rcp_f32_e32 v79, v79
	s_nop 0
	v_pk_mul_f32 v[78:79], v[80:81], v[78:79]
	s_nop 0
	v_pk_mul_f32 v[76:77], v[78:79], v[76:77]
	v_mul_f32_e32 v78, 0xbfb8aa3b, v70
	v_mul_f32_e32 v79, 0xbfb8aa3b, v71
	v_exp_f32_e32 v78, v78
	v_exp_f32_e32 v79, v79
	v_add_f32_e32 v78, 1.0, v78
	v_add_f32_e32 v79, 1.0, v79
	v_rcp_f32_e32 v78, v78
	v_rcp_f32_e32 v79, v79
	s_nop 0
	v_pk_mul_f32 v[70:71], v[70:71], v[78:79]
	s_nop 0
	v_pk_mul_f32 v[70:71], v[70:71], v[66:67]
	v_mul_f32_e32 v66, 0xbfb8aa3b, v72
	v_mul_f32_e32 v67, 0xbfb8aa3b, v73
	v_exp_f32_e32 v66, v66
	v_exp_f32_e32 v67, v67
	v_add_f32_e32 v66, 1.0, v66
	v_add_f32_e32 v67, 1.0, v67
	v_rcp_f32_e32 v66, v66
	v_rcp_f32_e32 v67, v67
	s_nop 0
	v_pk_mul_f32 v[66:67], v[72:73], v[66:67]
	s_nop 0
	v_pk_mul_f32 v[72:73], v[66:67], v[68:69]
	v_cvt_pk_bf16_f32 v68, v70, v71
	v_or_b32_e32 v70, 48, v145
	v_mad_i64_i32 v[70:71], s[20:21], v70, s7, v[114:115]
	v_cvt_pk_bf16_f32 v66, v74, v75
	v_cvt_pk_bf16_f32 v67, v76, v77
	v_cvt_pk_bf16_f32 v69, v72, v73
	v_lshl_add_u64 v[70:71], v[70:71], 0, v[116:117]
	global_store_dwordx4 v[70:71], v[66:69], off
	s_nop 1
	v_mul_f32_e32 v66, 0xbfb8aa3b, v62
	v_mul_f32_e32 v67, 0xbfb8aa3b, v63
	v_exp_f32_e32 v66, v66
	v_exp_f32_e32 v67, v67
	v_add_u32_e32 v68, 0x80, v145
	v_add_f32_e32 v66, 1.0, v66
	v_add_f32_e32 v67, 1.0, v67
	v_rcp_f32_e32 v66, v66
	v_rcp_f32_e32 v67, v67
	s_nop 0
	v_pk_mul_f32 v[62:63], v[62:63], v[66:67]
	s_nop 0
	v_pk_mul_f32 v[58:59], v[62:63], v[58:59]
	v_mul_f32_e32 v62, 0xbfb8aa3b, v64
	v_mul_f32_e32 v63, 0xbfb8aa3b, v65
	v_exp_f32_e32 v62, v62
	v_exp_f32_e32 v63, v63
	v_add_f32_e32 v62, 1.0, v62
	v_add_f32_e32 v63, 1.0, v63
	v_rcp_f32_e32 v62, v62
	v_rcp_f32_e32 v63, v63
	s_nop 0
	v_pk_mul_f32 v[62:63], v[64:65], v[62:63]
	s_nop 0
	v_pk_mul_f32 v[60:61], v[62:63], v[60:61]
	v_mul_f32_e32 v62, 0xbfb8aa3b, v54
	v_mul_f32_e32 v63, 0xbfb8aa3b, v55
	v_exp_f32_e32 v62, v62
	v_exp_f32_e32 v63, v63
	v_add_f32_e32 v62, 1.0, v62
	v_add_f32_e32 v63, 1.0, v63
	v_rcp_f32_e32 v62, v62
	v_rcp_f32_e32 v63, v63
	s_nop 0
	v_pk_mul_f32 v[54:55], v[54:55], v[62:63]
	s_nop 0
	v_pk_mul_f32 v[54:55], v[54:55], v[50:51]
	v_mul_f32_e32 v50, 0xbfb8aa3b, v56
	v_mul_f32_e32 v51, 0xbfb8aa3b, v57
	v_exp_f32_e32 v50, v50
	v_exp_f32_e32 v51, v51
	v_add_f32_e32 v50, 1.0, v50
	v_add_f32_e32 v51, 1.0, v51
	v_rcp_f32_e32 v50, v50
	v_rcp_f32_e32 v51, v51
	s_nop 0
	v_pk_mul_f32 v[50:51], v[56:57], v[50:51]
	s_nop 0
	v_pk_mul_f32 v[56:57], v[50:51], v[52:53]
	v_cvt_pk_bf16_f32 v52, v54, v55
	v_mad_i64_i32 v[54:55], s[20:21], v68, s7, v[114:115]
	v_cvt_pk_bf16_f32 v50, v58, v59
	v_cvt_pk_bf16_f32 v51, v60, v61
	v_cvt_pk_bf16_f32 v53, v56, v57
	v_lshl_add_u64 v[54:55], v[54:55], 0, v[116:117]
	global_store_dwordx4 v[54:55], v[50:53], off
	s_nop 1
	v_mul_f32_e32 v50, 0xbfb8aa3b, v46
	v_mul_f32_e32 v51, 0xbfb8aa3b, v47
	v_exp_f32_e32 v50, v50
	v_exp_f32_e32 v51, v51
	v_add_f32_e32 v50, 1.0, v50
	v_add_f32_e32 v51, 1.0, v51
	v_rcp_f32_e32 v50, v50
	v_rcp_f32_e32 v51, v51
	s_nop 0
	v_pk_mul_f32 v[46:47], v[46:47], v[50:51]
	s_nop 0
	v_pk_mul_f32 v[42:43], v[46:47], v[42:43]
	v_mul_f32_e32 v46, 0xbfb8aa3b, v48
	v_mul_f32_e32 v47, 0xbfb8aa3b, v49
	v_exp_f32_e32 v46, v46
	v_exp_f32_e32 v47, v47
	v_add_f32_e32 v46, 1.0, v46
	v_add_f32_e32 v47, 1.0, v47
	v_rcp_f32_e32 v46, v46
	v_rcp_f32_e32 v47, v47
	s_nop 0
	v_pk_mul_f32 v[46:47], v[48:49], v[46:47]
	s_nop 0
	v_pk_mul_f32 v[44:45], v[46:47], v[44:45]
	v_mul_f32_e32 v46, 0xbfb8aa3b, v38
	v_mul_f32_e32 v47, 0xbfb8aa3b, v39
	v_exp_f32_e32 v46, v46
	v_exp_f32_e32 v47, v47
	v_add_f32_e32 v46, 1.0, v46
	v_add_f32_e32 v47, 1.0, v47
	v_rcp_f32_e32 v46, v46
	v_rcp_f32_e32 v47, v47
	s_nop 0
	v_pk_mul_f32 v[38:39], v[38:39], v[46:47]
	s_nop 0
	v_pk_mul_f32 v[38:39], v[38:39], v[34:35]
	v_mul_f32_e32 v34, 0xbfb8aa3b, v40
	v_mul_f32_e32 v35, 0xbfb8aa3b, v41
	v_exp_f32_e32 v34, v34
	v_exp_f32_e32 v35, v35
	v_add_f32_e32 v34, 1.0, v34
	v_add_f32_e32 v35, 1.0, v35
	v_rcp_f32_e32 v34, v34
	v_rcp_f32_e32 v35, v35
	s_nop 0
	v_pk_mul_f32 v[34:35], v[40:41], v[34:35]
	s_nop 0
	v_pk_mul_f32 v[40:41], v[34:35], v[36:37]
	v_cvt_pk_bf16_f32 v36, v38, v39
	v_add_u32_e32 v38, 0x90, v145
	v_mad_i64_i32 v[38:39], s[20:21], v38, s7, v[114:115]
	v_cvt_pk_bf16_f32 v34, v42, v43
	v_cvt_pk_bf16_f32 v35, v44, v45
	v_cvt_pk_bf16_f32 v37, v40, v41
	v_lshl_add_u64 v[38:39], v[38:39], 0, v[116:117]
	global_store_dwordx4 v[38:39], v[34:37], off
	s_nop 1
	v_mul_f32_e32 v34, 0xbfb8aa3b, v30
	v_mul_f32_e32 v35, 0xbfb8aa3b, v31
	v_exp_f32_e32 v34, v34
	v_exp_f32_e32 v35, v35
	v_add_f32_e32 v34, 1.0, v34
	v_add_f32_e32 v35, 1.0, v35
	v_rcp_f32_e32 v34, v34
	v_rcp_f32_e32 v35, v35
	s_nop 0
	v_pk_mul_f32 v[30:31], v[30:31], v[34:35]
	s_nop 0
	v_pk_mul_f32 v[26:27], v[30:31], v[26:27]
	v_mul_f32_e32 v30, 0xbfb8aa3b, v32
	v_mul_f32_e32 v31, 0xbfb8aa3b, v33
	v_exp_f32_e32 v30, v30
	v_exp_f32_e32 v31, v31
	v_add_f32_e32 v30, 1.0, v30
	v_add_f32_e32 v31, 1.0, v31
	v_rcp_f32_e32 v30, v30
	v_rcp_f32_e32 v31, v31
	s_nop 0
	v_pk_mul_f32 v[30:31], v[32:33], v[30:31]
	s_nop 0
	v_pk_mul_f32 v[28:29], v[30:31], v[28:29]
	v_mul_f32_e32 v30, 0xbfb8aa3b, v22
	v_mul_f32_e32 v31, 0xbfb8aa3b, v23
	v_exp_f32_e32 v30, v30
	v_exp_f32_e32 v31, v31
	v_add_f32_e32 v30, 1.0, v30
	v_add_f32_e32 v31, 1.0, v31
	v_rcp_f32_e32 v30, v30
	v_rcp_f32_e32 v31, v31
	s_nop 0
	v_pk_mul_f32 v[22:23], v[22:23], v[30:31]
	s_nop 0
	v_pk_mul_f32 v[22:23], v[22:23], v[18:19]
	v_mul_f32_e32 v18, 0xbfb8aa3b, v24
	v_mul_f32_e32 v19, 0xbfb8aa3b, v25
	v_exp_f32_e32 v18, v18
	v_exp_f32_e32 v19, v19
	v_add_f32_e32 v18, 1.0, v18
	v_add_f32_e32 v19, 1.0, v19
	v_rcp_f32_e32 v18, v18
	v_rcp_f32_e32 v19, v19
	s_nop 0
	v_pk_mul_f32 v[18:19], v[24:25], v[18:19]
	s_nop 0
	v_pk_mul_f32 v[24:25], v[18:19], v[20:21]
	v_cvt_pk_bf16_f32 v20, v22, v23
	v_add_u32_e32 v22, 0xa0, v145
	v_mad_i64_i32 v[22:23], s[20:21], v22, s7, v[114:115]
	v_cvt_pk_bf16_f32 v18, v26, v27
	v_cvt_pk_bf16_f32 v19, v28, v29
	v_cvt_pk_bf16_f32 v21, v24, v25
	v_lshl_add_u64 v[22:23], v[22:23], 0, v[116:117]
	global_store_dwordx4 v[22:23], v[18:21], off
	s_nop 1
	v_mul_f32_e32 v18, 0xbfb8aa3b, v14
	v_mul_f32_e32 v19, 0xbfb8aa3b, v15
	v_exp_f32_e32 v18, v18
	v_exp_f32_e32 v19, v19
	v_add_f32_e32 v18, 1.0, v18
	v_add_f32_e32 v19, 1.0, v19
	v_rcp_f32_e32 v18, v18
	v_rcp_f32_e32 v19, v19
	s_nop 0
	v_pk_mul_f32 v[14:15], v[14:15], v[18:19]
	s_nop 0
	v_pk_mul_f32 v[10:11], v[14:15], v[10:11]
	v_mul_f32_e32 v14, 0xbfb8aa3b, v16
	v_mul_f32_e32 v15, 0xbfb8aa3b, v17
	v_exp_f32_e32 v14, v14
	v_exp_f32_e32 v15, v15
	v_add_f32_e32 v14, 1.0, v14
	v_add_f32_e32 v15, 1.0, v15
	v_rcp_f32_e32 v14, v14
	v_rcp_f32_e32 v15, v15
	s_nop 0
	v_pk_mul_f32 v[14:15], v[16:17], v[14:15]
	s_nop 0
	v_pk_mul_f32 v[12:13], v[14:15], v[12:13]
	v_mul_f32_e32 v14, 0xbfb8aa3b, v6
	v_mul_f32_e32 v15, 0xbfb8aa3b, v7
	v_exp_f32_e32 v14, v14
	v_exp_f32_e32 v15, v15
	v_add_f32_e32 v14, 1.0, v14
	v_add_f32_e32 v15, 1.0, v15
	v_rcp_f32_e32 v14, v14
	v_rcp_f32_e32 v15, v15
	s_nop 0
	v_pk_mul_f32 v[6:7], v[6:7], v[14:15]
	s_nop 0
	v_pk_mul_f32 v[6:7], v[6:7], v[2:3]
	v_mul_f32_e32 v2, 0xbfb8aa3b, v8
	v_mul_f32_e32 v3, 0xbfb8aa3b, v9
	v_exp_f32_e32 v2, v2
	v_exp_f32_e32 v3, v3
	v_add_f32_e32 v2, 1.0, v2
	v_add_f32_e32 v3, 1.0, v3
	v_rcp_f32_e32 v2, v2
	v_rcp_f32_e32 v3, v3
	s_nop 0
	v_pk_mul_f32 v[2:3], v[8:9], v[2:3]
	s_nop 0
	v_pk_mul_f32 v[8:9], v[2:3], v[4:5]
	v_cvt_pk_bf16_f32 v4, v6, v7
	v_add_u32_e32 v6, 0xb0, v145
	v_mad_i64_i32 v[6:7], s[20:21], v6, s7, v[114:115]
	v_cvt_pk_bf16_f32 v2, v10, v11
	v_cvt_pk_bf16_f32 v3, v12, v13
	v_cvt_pk_bf16_f32 v5, v8, v9
	v_lshl_add_u64 v[6:7], v[6:7], 0, v[116:117]
	s_mov_b64 s[20:21], s[12:13]
	global_store_dwordx4 v[6:7], v[2:5], off
	s_cbranch_vccz .LBB0_294
	s_waitcnt vmcnt(0)
	s_cmpk_gt_u32 s28, 0xff
	s_cbranch_scc1 .LBB0_301
	s_barrier
